# d4 + counted lgkmcnt waits in the attention QK section (each MFMA waits only for its own K fragment read)
# speedup vs baseline: 1.0159x; 1.0066x over previous
; __device__ __forceinline__ unsigned cvtpk(float lo, float hi) { f32x2 v = {lo, hi}; bf16x2_t b = __builtin_convertvector(v, bf16x2_t); return __builtin_bit_cast(unsigned, b); }
; __device__ __forceinline__ float fast_exp2(float x) { return __builtin_amdgcn_exp2f(x); }
; template <bool QK, bool PV> ...
;     ...
;     if constexpr (PV) { AT_TR4(0, 0); AT_TR4(1, 1);
;         const bf16x8 ones = (bf16x8){0x3f80, 0x3f80, 0x3f80, 0x3f80, 0x3f80, 0x3f80, 0x3f80, 0x3f80};
; #pragma unroll
;         for (int c = 0; c < 2; ++c)
; #pragma unroll
;             for (int si = 0; si < 2; ++si) ol[c] = __builtin_amdgcn_mfma_f32_16x16x32_bf16(ones, pf[c][si], ol[c], 0, 0, 0); }
; #pragma unroll
;     for (int dt = 0; dt < 8; ++dt) {
;         if constexpr (PV) {
;             const int cb = dt % 3;
;             if (dt < 6) { AT_TR4((dt + 2) % 3, dt + 2); asm volatile("s_waitcnt lgkmcnt(8)" : "+v"(r[cb][0]), "+v"(r[cb][1]), "+v"(r[cb][2]), "+v"(r[cb][3])); }
;             else if (dt == 6) asm volatile("s_waitcnt lgkmcnt(4)" : "+v"(r[cb][0]), "+v"(r[cb][1]), "+v"(r[cb][2]), "+v"(r[cb][3]));
;             else asm volatile("s_waitcnt lgkmcnt(0)" : "+v"(r[cb][0]), "+v"(r[cb][1]), "+v"(r[cb][2]), "+v"(r[cb][3]));
; #pragma unroll
;             for (int si = 0; si < 2; ++si) {
;                 const s16x4 lo = r[cb][2 * si], hi = r[cb][2 * si + 1];
;                 const bf16x8 vf = (bf16x8){lo[0], lo[1], lo[2], lo[3], hi[0], hi[1], hi[2], hi[3]};
;                 o[0][dt] = __builtin_amdgcn_mfma_f32_16x16x32_bf16(vf, pf[0][si], o[0][dt], 0, 0, 0);
;                 o[1][dt] = __builtin_amdgcn_mfma_f32_16x16x32_bf16(vf, pf[1][si], o[1][dt], 0, 0, 0);
;             }
;         }
;         {
;             const int c = dt >> 2, kt = dt & 3;
; #pragma unroll
;             for (int j = 0; j < 4; ++j) s[c][kt][j] = fast_exp2(s[c][kt][j]);
;             if (kt & 1) { const int si = kt >> 1;
;                 u32x4 wv; wv.x = cvtpk(s[c][2 * si][0], s[c][2 * si][1]); wv.y = cvtpk(s[c][2 * si][2], s[c][2 * si][3]);
;                 wv.z = cvtpk(s[c][2 * si + 1][0], s[c][2 * si + 1][1]); wv.w = cvtpk(s[c][2 * si + 1][2], s[c][2 * si + 1][3]);
;                 pn[c][si] = __builtin_bit_cast(bf16x8, wv); }
.LBB0_518:
	v_mov_b64_e32 v[218:219], s[6:7]
	v_mov_b64_e32 v[216:217], s[4:5]
	s_and_b32 s2, s55, 0xc000
	s_add_i32 s2, s2, 0
	s_add_i32 s2, s2, 0xc000
	v_add_u32_e32 v228, s2, v186
	v_mfma_f32_16x16x32_bf16 v[134:137], v[216:219], v[58:61], v[134:137]
	ds_read_b64_tr_b16 v[220:221], v228 offset:0
	ds_read_b64_tr_b16 v[222:223], v228 offset:0x1000
	ds_read_b64_tr_b16 v[224:225], v228 offset:0x2000
	v_mfma_f32_16x16x32_bf16 v[130:133], v[216:219], v[42:45], v[130:133]
	ds_read_b64_tr_b16 v[226:227], v228 offset:0x3000
	v_add_u32_e32 v236, s2, v187
	ds_read_b64_tr_b16 v[228:229], v236 offset:0
	v_mfma_f32_16x16x32_bf16 v[134:137], v[216:219], v[34:37], v[134:137]
	ds_read_b64_tr_b16 v[230:231], v236 offset:0x1000
	ds_read_b64_tr_b16 v[232:233], v236 offset:0x2000
	ds_read_b64_tr_b16 v[234:235], v236 offset:0x3000
	v_mfma_f32_16x16x32_bf16 v[130:133], v[216:219], v[18:21], v[130:133]
	v_add_u32_e32 v240, s2, v188
	ds_read_b64_tr_b16 v[216:217], v240 offset:0
	ds_read_b64_tr_b16 v[218:219], v240 offset:0x1000
	ds_read_b64_tr_b16 v[236:237], v240 offset:0x2000
	ds_read_b64_tr_b16 v[238:239], v240 offset:0x3000
	s_waitcnt lgkmcnt(8)
	v_add_u32_e32 v240, s2, v189
	v_mfma_f32_16x16x32_bf16 v[126:129], v[220:223], v[58:61], v[126:129]
	v_exp_f32_e32 v241, v28
	v_exp_f32_e32 v242, v29
	s_addk_i32 s55, 0x4000
	v_mfma_f32_16x16x32_bf16 v[122:125], v[220:223], v[42:45], v[122:125]
	ds_read_b64_tr_b16 v[220:221], v240 offset:0
	ds_read_b64_tr_b16 v[222:223], v240 offset:0x1000
	s_add_i32 s60, s60, 1
	v_mfma_f32_16x16x32_bf16 v[126:129], v[224:227], v[34:37], v[126:129]
	v_mfma_f32_16x16x32_bf16 v[122:125], v[224:227], v[18:21], v[122:125]
	ds_read_b64_tr_b16 v[224:225], v240 offset:0x2000
	ds_read_b64_tr_b16 v[226:227], v240 offset:0x3000
	s_waitcnt lgkmcnt(8)
	v_add_u32_e32 v240, s2, v190
	v_mfma_f32_16x16x32_bf16 v[114:117], v[228:231], v[58:61], v[114:117]
	v_mfma_f32_16x16x32_bf16 v[118:121], v[228:231], v[42:45], v[118:121]
	ds_read_b64_tr_b16 v[228:229], v240 offset:0
	ds_read_b64_tr_b16 v[230:231], v240 offset:0x1000
	v_mfma_f32_16x16x32_bf16 v[114:117], v[232:235], v[34:37], v[114:117]
	v_mfma_f32_16x16x32_bf16 v[118:121], v[232:235], v[18:21], v[118:121]
	ds_read_b64_tr_b16 v[232:233], v240 offset:0x2000
	ds_read_b64_tr_b16 v[234:235], v240 offset:0x3000
	s_waitcnt lgkmcnt(8)
	v_add_u32_e32 v240, s2, v191
	v_mfma_f32_16x16x32_bf16 v[106:109], v[216:219], v[58:61], v[106:109]
	v_mfma_f32_16x16x32_bf16 v[110:113], v[216:219], v[42:45], v[110:113]
	ds_read_b64_tr_b16 v[216:217], v240 offset:0
	ds_read_b64_tr_b16 v[218:219], v240 offset:0x1000
	v_mfma_f32_16x16x32_bf16 v[106:109], v[236:239], v[34:37], v[106:109]
	v_mfma_f32_16x16x32_bf16 v[110:113], v[236:239], v[18:21], v[110:113]
	ds_read_b64_tr_b16 v[236:237], v240 offset:0x2000
	ds_read_b64_tr_b16 v[238:239], v240 offset:0x3000
	s_waitcnt lgkmcnt(8)
	v_add_u32_e32 v240, s2, v192
	v_mfma_f32_16x16x32_bf16 v[98:101], v[220:223], v[58:61], v[98:101]
	v_mfma_f32_16x16x32_bf16 v[102:105], v[220:223], v[42:45], v[102:105]
	ds_read_b64_tr_b16 v[220:221], v240 offset:0
	ds_read_b64_tr_b16 v[222:223], v240 offset:0x1000
	v_mfma_f32_16x16x32_bf16 v[98:101], v[224:227], v[34:37], v[98:101]
	v_mfma_f32_16x16x32_bf16 v[102:105], v[224:227], v[18:21], v[102:105]
	ds_read_b64_tr_b16 v[224:225], v240 offset:0x2000
	ds_read_b64_tr_b16 v[226:227], v240 offset:0x3000
	s_waitcnt lgkmcnt(8)
	v_add_u32_e32 v240, s2, v193
	v_mfma_f32_16x16x32_bf16 v[78:81], v[228:231], v[58:61], v[78:81]
	s_add_i32 s2, s61, 0
	s_cmp_lg_u32 s54, s60
	v_mfma_f32_16x16x32_bf16 v[82:85], v[228:231], v[42:45], v[82:85]
	ds_read_b64_tr_b16 v[228:229], v240 offset:0
	ds_read_b64_tr_b16 v[230:231], v240 offset:0x1000
	v_mfma_f32_16x16x32_bf16 v[78:81], v[232:235], v[34:37], v[78:81]
	v_mfma_f32_16x16x32_bf16 v[82:85], v[232:235], v[18:21], v[82:85]
	ds_read_b64_tr_b16 v[232:233], v240 offset:0x2000
	ds_read_b64_tr_b16 v[234:235], v240 offset:0x3000
	s_waitcnt lgkmcnt(8)
	s_waitcnt lgkmcnt(4)
	v_exp_f32_e32 v240, v22
	v_mfma_f32_16x16x32_bf16 v[54:57], v[220:223], v[58:61], v[54:57]
	s_waitcnt lgkmcnt(0)
	s_barrier
; #define LAS __attribute__((address_space(3)))
; #define AT_STAGE(gbase, so, i, ldsoff) do { const int _ii = (i) < NT ? (i) : NT - 1; const size_t _go = (size_t)((tstart + _ii) & tmask) * (64 * 1024); _Pragma("unroll") for (int _i = 0; _i < 2; ++_i) \
;         __builtin_amdgcn_global_load_lds((const unsigned*)((gbase) + _go + (so)[_i]), (LAS unsigned*)(lds + (ldsoff) + (2 * w + _i) * 1024), 16, 0, 0); } while (0)
; #define AT_BAR(N) asm volatile("s_waitcnt vmcnt(" #N ") lgkmcnt(0)\n\ts_barrier" ::: "memory")
; template <bool QK, bool PV> ...
;     ...
;     for (int c = 0; c < 2; ++c)
; #pragma unroll
;         for (int si = 0; si < 2; ++si) pf[c][si] = pn[c][si];
;     if constexpr (QK) {
; #pragma unroll
;         for (int kt = 0; kt < 4; ++kt)
; #pragma unroll
;             for (int c = 0; c < 2; ++c) {
;                 f32x4 a = tbv[kt];
; #pragma unroll
;                 for (int kk = 0; kk < 2; ++kk) { const bf16x8 kf = *(const LAS bf16x8*)(kbuf + kfo[c][kk] + kt * 4096); a = __builtin_amdgcn_mfma_f32_16x16x32_bf16(kf, qf[c][kk], a, 0, 0, 0); }
;                 s[c][kt] = a;
;             }
;     }
; __device__ __forceinline__ void attn_unit(LAS unsigned char* lds, int seq, int h, int qb, bf16_t* UQ, const bf16_t* KB, const bf16_t* VB, const float* rel_bias, const float* subln, float lam, float bmax) {
;     ...
;     for (int i = 1; i < NT - 1; ++i) {
;         AT_STAGE(kg, kso, i + 3, k_i); AT_STAGE(vg, vso, i + 2, AT_V0 + ((i + 2) & 3) * AT_TILE);
;         AT_TB((tstart + i + 1) & tmask);
;         attn_step<true, true>(lds + k_n, lds0 + AT_V0 + ((i - 1) & 3) * AT_TILE, kfo, vo, qf, s, pf, o, ol, tbv);
;         AT_BAR(4);
;         { const int tmp = k_i; k_i = k_n; k_n = k_p; k_p = tmp; }
	s_add_i32 s99, s60, 3
	s_min_u32 s99, s99, s45
	s_add_i32 s99, s99, s46
	s_and_b32 s99, s99, s45
	s_lshl_b32 s99, s99, 16
	s_add_u32 s100, s47, s99
	s_addc_u32 s101, s48, 0
	s_add_i32 s99, s49, s59
	s_mov_b32 m0, s99
	s_nop 0
	global_load_lds_dwordx4 v154, s[100:101]
	s_add_i32 m0, s99, 0x400
	s_nop 0
	global_load_lds_dwordx4 v166, s[100:101]
	s_cmp_lg_u32 s54, s60
	v_mfma_f32_16x16x32_bf16 v[50:53], v[220:223], v[42:45], v[50:53]
	v_exp_f32_e32 v220, v88
	v_exp_f32_e32 v221, v89
	v_exp_f32_e32 v222, v90
	v_mfma_f32_16x16x32_bf16 v[54:57], v[224:227], v[34:37], v[54:57]
	v_exp_f32_e32 v223, v91
	v_mfma_f32_16x16x32_bf16 v[50:53], v[224:227], v[18:21], v[50:53]
	v_exp_f32_e32 v224, v94
	v_add_u32_e32 v94, s2, v182
	v_exp_f32_e32 v225, v95
	v_mfma_f32_16x16x32_bf16 v[66:69], v[216:219], v[58:61], v[66:69]
	v_exp_f32_e32 v226, v96
	v_exp_f32_e32 v95, v38
	v_exp_f32_e32 v96, v39
	v_mfma_f32_16x16x32_bf16 v[30:33], v[228:231], v[58:61], v[30:33]
	ds_read_b128 v[58:61], v94
	v_exp_f32_e32 v227, v97
	v_mfma_f32_16x16x32_bf16 v[70:73], v[216:219], v[42:45], v[70:73]
	v_exp_f32_e32 v216, v74
	v_exp_f32_e32 v217, v75
	v_exp_f32_e32 v218, v76
	v_mfma_f32_16x16x32_bf16 v[42:45], v[228:231], v[42:45], v[46:49]
	v_add_u32_e32 v230, s2, v183
	v_add_u32_e32 v231, s2, v184
	v_exp_f32_e32 v219, v77
	v_mfma_f32_16x16x32_bf16 v[66:69], v[236:239], v[34:37], v[66:69]
	v_exp_f32_e32 v228, v23
	v_exp_f32_e32 v229, v24
	v_mfma_f32_16x16x32_bf16 v[30:33], v[232:235], v[34:37], v[30:33]
	ds_read_b128 v[34:37], v230
	s_waitcnt lgkmcnt(1)
	v_mfma_f32_16x16x32_bf16 v[58:61], v[58:61], v[2:5], v[146:149]
	v_mfma_f32_16x16x32_bf16 v[70:73], v[236:239], v[18:21], v[70:73]
	v_exp_f32_e32 v236, v86
	v_exp_f32_e32 v237, v87
	v_exp_f32_e32 v238, v92
	v_mfma_f32_16x16x32_bf16 v[46:49], v[232:235], v[18:21], v[42:45]
	ds_read_b128 v[18:21], v231
	s_nop 1
	ds_read_b128 v[42:45], v94 offset:4096
	v_add_u32_e32 v232, s2, v185
	v_exp_f32_e32 v239, v93
	ds_read_b128 v[86:89], v232
	ds_read_b128 v[90:93], v230 offset:4096
	s_waitcnt lgkmcnt(4)
	v_mfma_f32_16x16x32_bf16 v[74:77], v[34:37], v[6:9], v[58:61]
	ds_read_b128 v[34:37], v231 offset:4096
	v_exp_f32_e32 v233, v25
	v_exp_f32_e32 v234, v26
	s_waitcnt lgkmcnt(4)
	v_mfma_f32_16x16x32_bf16 v[18:21], v[18:21], v[10:13], v[146:149]
	ds_read_b128 v[58:61], v232 offset:4096
	v_exp_f32_e32 v235, v27
	s_waitcnt lgkmcnt(3)
	v_mfma_f32_16x16x32_bf16 v[22:25], v[86:89], v[14:17], v[18:21]
	v_mfma_f32_16x16x32_bf16 v[18:21], v[42:45], v[2:5], v[138:141]
	v_exp_f32_e32 v42, v40
	v_exp_f32_e32 v43, v41
	ds_read_b128 v[38:41], v94 offset:8192
	s_waitcnt lgkmcnt(2)
	v_mfma_f32_16x16x32_bf16 v[26:29], v[34:37], v[10:13], v[138:141]
	ds_read_b128 v[34:37], v230 offset:8192
	v_exp_f32_e32 v44, v62
	v_exp_f32_e32 v45, v65
	v_mfma_f32_16x16x32_bf16 v[86:89], v[90:93], v[6:9], v[18:21]
	s_nop 2
	v_exp_f32_e32 v20, v63
	v_exp_f32_e32 v21, v64
	v_cvt_pk_bf16_f32 v18, v95, v96
	s_waitcnt lgkmcnt(2)
	v_mfma_f32_16x16x32_bf16 v[26:29], v[58:61], v[14:17], v[26:29]
	ds_read_b128 v[58:61], v231 offset:8192
	ds_read_b128 v[62:65], v94 offset:12288
	ds_read_b128 v[94:97], v232 offset:8192
	ds_read_b128 v[138:141], v230 offset:12288
	ds_read_b128 v[146:149], v231 offset:12288
	s_waitcnt lgkmcnt(6)
	v_mfma_f32_16x16x32_bf16 v[38:41], v[38:41], v[2:5], v[150:153]
	v_cvt_pk_bf16_f32 v19, v42, v43
	v_cvt_pk_bf16_f32 v20, v44, v20
	v_cvt_pk_bf16_f32 v21, v21, v45
	s_waitcnt lgkmcnt(5)
	v_mfma_f32_16x16x32_bf16 v[90:93], v[34:37], v[6:9], v[38:41]
	v_cvt_pk_bf16_f32 v42, v240, v228
	v_cvt_pk_bf16_f32 v43, v229, v233
	v_cvt_pk_bf16_f32 v44, v234, v235
	s_waitcnt lgkmcnt(4)
	v_mfma_f32_16x16x32_bf16 v[34:37], v[58:61], v[10:13], v[150:153]
	v_cvt_pk_bf16_f32 v45, v241, v242
	v_cvt_pk_bf16_f32 v58, v216, v217
	v_cvt_pk_bf16_f32 v59, v218, v219
	ds_read_b128 v[150:153], v232 offset:12288
	s_waitcnt lgkmcnt(4)
	v_mfma_f32_16x16x32_bf16 v[60:63], v[62:65], v[2:5], v[142:145]
	s_waitcnt vmcnt(4) lgkmcnt(0)
	s_barrier
	v_mfma_f32_16x16x32_bf16 v[38:41], v[94:97], v[14:17], v[34:37]
	v_mfma_f32_16x16x32_bf16 v[94:97], v[138:141], v[6:9], v[60:63]
	s_nop 1
	v_cvt_pk_bf16_f32 v34, v222, v223
	v_cvt_pk_bf16_f32 v35, v238, v239
	v_cvt_pk_bf16_f32 v36, v224, v225
	v_mfma_f32_16x16x32_bf16 v[62:65], v[146:149], v[10:13], v[142:145]
	v_cvt_pk_bf16_f32 v37, v226, v227
	v_cvt_pk_bf16_f32 v60, v236, v237
	v_cvt_pk_bf16_f32 v61, v220, v221
	v_mfma_f32_16x16x32_bf16 v[62:65], v[150:153], v[14:17], v[62:65]
	s_cbranch_scc0 .LBB0_502
	s_mov_b32 s2, s59
	s_mov_b32 s59, s61
	s_branch .LBB0_514

; __device__ __forceinline__ unsigned cvtpk(float lo, float hi) { f32x2 v = {lo, hi}; bf16x2_t b = __builtin_convertvector(v, bf16x2_t); return __builtin_bit_cast(unsigned, b); }
; __device__ __forceinline__ float fast_exp2(float x) { return __builtin_amdgcn_exp2f(x); }
; template <bool QK, bool PV> ...
;     ...
;     if constexpr (PV) { AT_TR4(0, 0); AT_TR4(1, 1);
;         const bf16x8 ones = (bf16x8){0x3f80, 0x3f80, 0x3f80, 0x3f80, 0x3f80, 0x3f80, 0x3f80, 0x3f80};
; #pragma unroll
;         for (int c = 0; c < 2; ++c)
; #pragma unroll
;             for (int si = 0; si < 2; ++si) ol[c] = __builtin_amdgcn_mfma_f32_16x16x32_bf16(ones, pf[c][si], ol[c], 0, 0, 0); }
; #pragma unroll
;     for (int dt = 0; dt < 8; ++dt) {
;         if constexpr (PV) {
;             const int cb = dt % 3;
;             if (dt < 6) { AT_TR4((dt + 2) % 3, dt + 2); asm volatile("s_waitcnt lgkmcnt(8)" : "+v"(r[cb][0]), "+v"(r[cb][1]), "+v"(r[cb][2]), "+v"(r[cb][3])); }
;             else if (dt == 6) asm volatile("s_waitcnt lgkmcnt(4)" : "+v"(r[cb][0]), "+v"(r[cb][1]), "+v"(r[cb][2]), "+v"(r[cb][3]));
;             else asm volatile("s_waitcnt lgkmcnt(0)" : "+v"(r[cb][0]), "+v"(r[cb][1]), "+v"(r[cb][2]), "+v"(r[cb][3]));
; #pragma unroll
;             for (int si = 0; si < 2; ++si) {
;                 const s16x4 lo = r[cb][2 * si], hi = r[cb][2 * si + 1];
;                 const bf16x8 vf = (bf16x8){lo[0], lo[1], lo[2], lo[3], hi[0], hi[1], hi[2], hi[3]};
;                 o[0][dt] = __builtin_amdgcn_mfma_f32_16x16x32_bf16(vf, pf[0][si], o[0][dt], 0, 0, 0);
;                 o[1][dt] = __builtin_amdgcn_mfma_f32_16x16x32_bf16(vf, pf[1][si], o[1][dt], 0, 0, 0);
;             }
;         }
;         {
;             const int c = dt >> 2, kt = dt & 3;
; #pragma unroll
;             for (int j = 0; j < 4; ++j) s[c][kt][j] = fast_exp2(s[c][kt][j]);
;             if (kt & 1) { const int si = kt >> 1;
;                 u32x4 wv; wv.x = cvtpk(s[c][2 * si][0], s[c][2 * si][1]); wv.y = cvtpk(s[c][2 * si][2], s[c][2 * si][3]);
;                 wv.z = cvtpk(s[c][2 * si + 1][0], s[c][2 * si + 1][1]); wv.w = cvtpk(s[c][2 * si + 1][2], s[c][2 * si + 1][3]);
;                 pn[c][si] = __builtin_bit_cast(bf16x8, wv); }
.LBB0_538:
	v_mov_b64_e32 v[220:221], s[6:7]
	v_mov_b64_e32 v[218:219], s[4:5]
	s_and_b32 s2, s53, 0xc000
	s_add_i32 s2, s2, 0
	s_add_i32 s2, s2, 0xc000
	v_add_u32_e32 v217, s2, v175
	v_mfma_f32_16x16x32_bf16 v[134:137], v[218:221], v[58:61], v[134:137]
	ds_read_b64_tr_b16 v[222:223], v217 offset:0
	ds_read_b64_tr_b16 v[224:225], v217 offset:0x1000
	ds_read_b64_tr_b16 v[226:227], v217 offset:0x2000
	v_mfma_f32_16x16x32_bf16 v[130:133], v[218:221], v[42:45], v[130:133]
	ds_read_b64_tr_b16 v[228:229], v217 offset:0x3000
	v_add_u32_e32 v217, s2, v185
	ds_read_b64_tr_b16 v[230:231], v217 offset:0
	v_mfma_f32_16x16x32_bf16 v[134:137], v[218:221], v[34:37], v[134:137]
	ds_read_b64_tr_b16 v[232:233], v217 offset:0x1000
	ds_read_b64_tr_b16 v[234:235], v217 offset:0x2000
	ds_read_b64_tr_b16 v[236:237], v217 offset:0x3000
	v_mfma_f32_16x16x32_bf16 v[130:133], v[218:221], v[18:21], v[130:133]
	v_add_u32_e32 v217, s2, v186
	ds_read_b64_tr_b16 v[218:219], v217 offset:0
	ds_read_b64_tr_b16 v[220:221], v217 offset:0x1000
	ds_read_b64_tr_b16 v[238:239], v217 offset:0x2000
	ds_read_b64_tr_b16 v[240:241], v217 offset:0x3000
	s_waitcnt lgkmcnt(8)
	v_add_u32_e32 v217, s2, v187
	v_mfma_f32_16x16x32_bf16 v[126:129], v[222:225], v[58:61], v[126:129]
	v_exp_f32_e32 v242, v28
	v_exp_f32_e32 v243, v29
	s_addk_i32 s53, 0x4000
	v_mfma_f32_16x16x32_bf16 v[122:125], v[222:225], v[42:45], v[122:125]
	ds_read_b64_tr_b16 v[222:223], v217 offset:0
	ds_read_b64_tr_b16 v[224:225], v217 offset:0x1000
	v_mfma_f32_16x16x32_bf16 v[126:129], v[226:229], v[34:37], v[126:129]
	v_mfma_f32_16x16x32_bf16 v[122:125], v[226:229], v[18:21], v[122:125]
	ds_read_b64_tr_b16 v[226:227], v217 offset:0x2000
	ds_read_b64_tr_b16 v[228:229], v217 offset:0x3000
	s_waitcnt lgkmcnt(8)
	v_add_u32_e32 v217, s2, v188
	v_mfma_f32_16x16x32_bf16 v[114:117], v[230:233], v[58:61], v[114:117]
	v_mfma_f32_16x16x32_bf16 v[118:121], v[230:233], v[42:45], v[118:121]
	ds_read_b64_tr_b16 v[230:231], v217 offset:0
	ds_read_b64_tr_b16 v[232:233], v217 offset:0x1000
	v_mfma_f32_16x16x32_bf16 v[114:117], v[234:237], v[34:37], v[114:117]
	v_mfma_f32_16x16x32_bf16 v[118:121], v[234:237], v[18:21], v[118:121]
	ds_read_b64_tr_b16 v[234:235], v217 offset:0x2000
	ds_read_b64_tr_b16 v[236:237], v217 offset:0x3000
	s_waitcnt lgkmcnt(8)
	v_add_u32_e32 v217, s2, v189
	v_mfma_f32_16x16x32_bf16 v[106:109], v[218:221], v[58:61], v[106:109]
	v_mfma_f32_16x16x32_bf16 v[110:113], v[218:221], v[42:45], v[110:113]
	ds_read_b64_tr_b16 v[218:219], v217 offset:0
	ds_read_b64_tr_b16 v[220:221], v217 offset:0x1000
	v_mfma_f32_16x16x32_bf16 v[106:109], v[238:241], v[34:37], v[106:109]
	v_mfma_f32_16x16x32_bf16 v[110:113], v[238:241], v[18:21], v[110:113]
	ds_read_b64_tr_b16 v[238:239], v217 offset:0x2000
	ds_read_b64_tr_b16 v[240:241], v217 offset:0x3000
	s_waitcnt lgkmcnt(8)
	v_add_u32_e32 v217, s2, v190
	v_mfma_f32_16x16x32_bf16 v[98:101], v[222:225], v[58:61], v[98:101]
	v_mfma_f32_16x16x32_bf16 v[102:105], v[222:225], v[42:45], v[102:105]
	ds_read_b64_tr_b16 v[222:223], v217 offset:0
	ds_read_b64_tr_b16 v[224:225], v217 offset:0x1000
	v_mfma_f32_16x16x32_bf16 v[98:101], v[226:229], v[34:37], v[98:101]
	v_mfma_f32_16x16x32_bf16 v[102:105], v[226:229], v[18:21], v[102:105]
	ds_read_b64_tr_b16 v[226:227], v217 offset:0x2000
	ds_read_b64_tr_b16 v[228:229], v217 offset:0x3000
	s_waitcnt lgkmcnt(8)
	v_add_u32_e32 v217, s2, v191
	v_mfma_f32_16x16x32_bf16 v[78:81], v[230:233], v[58:61], v[78:81]
	s_add_i32 s2, s57, 0
	s_cmp_lg_u32 s56, 30
	v_mfma_f32_16x16x32_bf16 v[82:85], v[230:233], v[42:45], v[82:85]
	ds_read_b64_tr_b16 v[230:231], v217 offset:0
	ds_read_b64_tr_b16 v[232:233], v217 offset:0x1000
	v_mfma_f32_16x16x32_bf16 v[78:81], v[234:237], v[34:37], v[78:81]
	v_mfma_f32_16x16x32_bf16 v[82:85], v[234:237], v[18:21], v[82:85]
	ds_read_b64_tr_b16 v[234:235], v217 offset:0x2000
	ds_read_b64_tr_b16 v[236:237], v217 offset:0x3000
	s_waitcnt lgkmcnt(8)
	s_waitcnt lgkmcnt(4)
	v_exp_f32_e32 v217, v74
	v_mfma_f32_16x16x32_bf16 v[54:57], v[222:225], v[58:61], v[54:57]
	s_waitcnt lgkmcnt(0)
	s_barrier
; #define LAS __attribute__((address_space(3)))
; #define AT_STAGE(gbase, so, i, ldsoff) do { const int _ii = (i) < NT ? (i) : NT - 1; const size_t _go = (size_t)((tstart + _ii) & tmask) * (64 * 1024); _Pragma("unroll") for (int _i = 0; _i < 2; ++_i) \
;         __builtin_amdgcn_global_load_lds((const unsigned*)((gbase) + _go + (so)[_i]), (LAS unsigned*)(lds + (ldsoff) + (2 * w + _i) * 1024), 16, 0, 0); } while (0)
; #define AT_BAR(N) asm volatile("s_waitcnt vmcnt(" #N ") lgkmcnt(0)\n\ts_barrier" ::: "memory")
; template <bool QK, bool PV> ...
;     ...
;     for (int c = 0; c < 2; ++c)
; #pragma unroll
;         for (int si = 0; si < 2; ++si) pf[c][si] = pn[c][si];
;     if constexpr (QK) {
; #pragma unroll
;         for (int kt = 0; kt < 4; ++kt)
; #pragma unroll
;             for (int c = 0; c < 2; ++c) {
;                 f32x4 a = tbv[kt];
; #pragma unroll
;                 for (int kk = 0; kk < 2; ++kk) { const bf16x8 kf = *(const LAS bf16x8*)(kbuf + kfo[c][kk] + kt * 4096); a = __builtin_amdgcn_mfma_f32_16x16x32_bf16(kf, qf[c][kk], a, 0, 0, 0); }
;                 s[c][kt] = a;
;             }
;     }
; __device__ __forceinline__ void attn_unit(LAS unsigned char* lds, int seq, int h, int qb, bf16_t* UQ, const bf16_t* KB, const bf16_t* VB, const float* rel_bias, const float* subln, float lam, float bmax) {
;     ...
;     for (int i = 1; i < NT - 1; ++i) {
;         AT_STAGE(kg, kso, i + 3, k_i); AT_STAGE(vg, vso, i + 2, AT_V0 + ((i + 2) & 3) * AT_TILE);
;         AT_TB((tstart + i + 1) & tmask);
;         attn_step<true, true>(lds + k_n, lds0 + AT_V0 + ((i - 1) & 3) * AT_TILE, kfo, vo, qf, s, pf, o, ol, tbv);
;         AT_BAR(4);
;         { const int tmp = k_i; k_i = k_n; k_n = k_p; k_p = tmp; }
	s_min_u32 s99, s56, 28
	s_add_i32 s99, s52, s99
	s_lshl_b32 s99, s99, 16
	s_and_b32 s99, s99, 0x1f0000
	s_add_u32 s100, s45, s99
	s_addc_u32 s101, s46, 0
	s_add_i32 s99, s47, s55
	s_mov_b32 m0, s99
	s_nop 0
	global_load_lds_dwordx4 v154, s[100:101]
	s_add_i32 m0, s99, 0x400
	s_nop 0
	global_load_lds_dwordx4 v166, s[100:101]
	s_cmp_lg_u32 s56, 30
	v_mfma_f32_16x16x32_bf16 v[50:53], v[222:225], v[42:45], v[50:53]
	v_exp_f32_e32 v222, v88
	v_exp_f32_e32 v223, v89
	v_exp_f32_e32 v224, v90
	v_mfma_f32_16x16x32_bf16 v[54:57], v[226:229], v[34:37], v[54:57]
	v_exp_f32_e32 v225, v91
	v_mfma_f32_16x16x32_bf16 v[50:53], v[226:229], v[18:21], v[50:53]
	v_exp_f32_e32 v226, v94
	v_add_u32_e32 v94, s2, v176
	v_exp_f32_e32 v227, v95
	v_mfma_f32_16x16x32_bf16 v[66:69], v[218:221], v[58:61], v[66:69]
	v_exp_f32_e32 v228, v96
	v_exp_f32_e32 v95, v38
	v_exp_f32_e32 v96, v39
	v_mfma_f32_16x16x32_bf16 v[30:33], v[230:233], v[58:61], v[30:33]
	ds_read_b128 v[58:61], v94
	v_exp_f32_e32 v229, v97
	v_mfma_f32_16x16x32_bf16 v[70:73], v[218:221], v[42:45], v[70:73]
	v_exp_f32_e32 v218, v75
	v_exp_f32_e32 v219, v76
	v_exp_f32_e32 v220, v77
	v_mfma_f32_16x16x32_bf16 v[42:45], v[230:233], v[42:45], v[46:49]
	v_add_u32_e32 v232, s2, v182
	v_add_u32_e32 v233, s2, v183
	v_exp_f32_e32 v221, v86
	v_mfma_f32_16x16x32_bf16 v[66:69], v[238:241], v[34:37], v[66:69]
	v_exp_f32_e32 v230, v23
	v_exp_f32_e32 v231, v24
	v_mfma_f32_16x16x32_bf16 v[30:33], v[234:237], v[34:37], v[30:33]
	ds_read_b128 v[34:37], v232
	s_waitcnt lgkmcnt(1)
	v_mfma_f32_16x16x32_bf16 v[58:61], v[58:61], v[2:5], v[146:149]
	v_mfma_f32_16x16x32_bf16 v[70:73], v[238:241], v[18:21], v[70:73]
	v_exp_f32_e32 v238, v87
	v_exp_f32_e32 v239, v92
	v_exp_f32_e32 v240, v93
	v_mfma_f32_16x16x32_bf16 v[46:49], v[234:237], v[18:21], v[42:45]
	ds_read_b128 v[18:21], v233
	s_nop 1
	ds_read_b128 v[42:45], v94 offset:4096
	v_add_u32_e32 v234, s2, v184
	ds_read_b128 v[86:89], v234
	ds_read_b128 v[90:93], v232 offset:4096
	s_waitcnt lgkmcnt(4)
	v_mfma_f32_16x16x32_bf16 v[74:77], v[34:37], v[6:9], v[58:61]
	ds_read_b128 v[34:37], v233 offset:4096
	v_exp_f32_e32 v241, v22
	v_exp_f32_e32 v235, v25
	s_waitcnt lgkmcnt(4)
	v_mfma_f32_16x16x32_bf16 v[18:21], v[18:21], v[10:13], v[146:149]
	ds_read_b128 v[58:61], v234 offset:4096
	v_exp_f32_e32 v236, v26
	v_exp_f32_e32 v237, v27
	s_waitcnt lgkmcnt(3)
	v_mfma_f32_16x16x32_bf16 v[22:25], v[86:89], v[14:17], v[18:21]
	v_mfma_f32_16x16x32_bf16 v[18:21], v[42:45], v[2:5], v[138:141]
	v_exp_f32_e32 v42, v40
	v_exp_f32_e32 v43, v41
	ds_read_b128 v[38:41], v94 offset:8192
	s_waitcnt lgkmcnt(2)
	v_mfma_f32_16x16x32_bf16 v[26:29], v[34:37], v[10:13], v[138:141]
	ds_read_b128 v[34:37], v232 offset:8192
	v_exp_f32_e32 v44, v62
	v_exp_f32_e32 v45, v65
	v_mfma_f32_16x16x32_bf16 v[86:89], v[90:93], v[6:9], v[18:21]
	s_nop 2
	v_exp_f32_e32 v20, v63
	v_exp_f32_e32 v21, v64
	v_cvt_pk_bf16_f32 v18, v95, v96
	s_waitcnt lgkmcnt(2)
	v_mfma_f32_16x16x32_bf16 v[26:29], v[58:61], v[14:17], v[26:29]
	ds_read_b128 v[58:61], v233 offset:8192
	ds_read_b128 v[62:65], v94 offset:12288
	ds_read_b128 v[94:97], v234 offset:8192
	ds_read_b128 v[138:141], v232 offset:12288
	ds_read_b128 v[146:149], v233 offset:12288
	s_waitcnt lgkmcnt(6)
	v_mfma_f32_16x16x32_bf16 v[38:41], v[38:41], v[2:5], v[150:153]
	v_cvt_pk_bf16_f32 v19, v42, v43
	v_cvt_pk_bf16_f32 v20, v44, v20
	v_cvt_pk_bf16_f32 v21, v21, v45
	s_waitcnt lgkmcnt(5)
	v_mfma_f32_16x16x32_bf16 v[90:93], v[34:37], v[6:9], v[38:41]
	v_cvt_pk_bf16_f32 v42, v241, v230
	v_cvt_pk_bf16_f32 v43, v231, v235
	v_cvt_pk_bf16_f32 v44, v236, v237
	s_waitcnt lgkmcnt(4)
	v_mfma_f32_16x16x32_bf16 v[34:37], v[58:61], v[10:13], v[150:153]
	v_cvt_pk_bf16_f32 v45, v242, v243
	v_cvt_pk_bf16_f32 v58, v217, v218
	v_cvt_pk_bf16_f32 v59, v219, v220
	ds_read_b128 v[150:153], v234 offset:12288
	s_waitcnt lgkmcnt(4)
	v_mfma_f32_16x16x32_bf16 v[60:63], v[62:65], v[2:5], v[142:145]
	s_waitcnt vmcnt(4) lgkmcnt(0)
	s_barrier
	v_mfma_f32_16x16x32_bf16 v[38:41], v[94:97], v[14:17], v[34:37]
	v_mfma_f32_16x16x32_bf16 v[94:97], v[138:141], v[6:9], v[60:63]
	s_nop 1
	v_cvt_pk_bf16_f32 v34, v224, v225
	v_cvt_pk_bf16_f32 v35, v239, v240
	v_cvt_pk_bf16_f32 v36, v226, v227
	v_mfma_f32_16x16x32_bf16 v[62:65], v[146:149], v[10:13], v[142:145]
	v_cvt_pk_bf16_f32 v37, v228, v229
	v_cvt_pk_bf16_f32 v60, v221, v238
	v_cvt_pk_bf16_f32 v61, v222, v223
	v_mfma_f32_16x16x32_bf16 v[62:65], v[150:153], v[14:17], v[62:65]
	s_cbranch_scc0 .LBB0_522
	s_mov_b32 s2, s55
	s_mov_b32 s55, s57
	s_branch .LBB0_534
